# P5 epilogue: 16 bf16 residual base loads hoisted to epilogue start with counted vmcnt(15) waits
# baseline (speedup 1.0000x reference)
; __device__ __forceinline__ unsigned pk2(float lo, float hi) { return pg8::cvt_pk_bf16(lo, hi); }
;     __device__ __forceinline__ void operator()(const f32x4 (&acc)[2][2][4][2], const pg8::Unit& u, int wr, int wc, int fr, int fq) const {
;     ...
;                 const int row = row0 + ai * 128 + m * 16; float ss = 0.f;
; #pragma unroll
;                 for (int bj = 0; bj < 2; ++bj) {
;                     const size_t off = (size_t)row * DM + col0 + bj * 128;
;                     float o[8];
;                     if (BASE_BF16) { const u32x4 bw = *(const u32x4*)((const bf16_t*)base + off);
; #pragma unroll
;                         for (int e = 0; e < 4; ++e) { o[2 * e] = __uint_as_float(bw[e] << 16); o[2 * e + 1] = __uint_as_float(bw[e] & 0xffff0000u); } }
;                     else { const f32x4 b0 = *(const f32x4*)((const float*)base + off), b1 = *(const f32x4*)((const float*)base + off + 4);
; #pragma unroll
;                         for (int e = 0; e < 4; ++e) { o[e] = b0[e]; o[4 + e] = b1[e]; } }
; #pragma unroll
;                     for (int n = 0; n < 2; ++n)
; #pragma unroll
;                         for (int e = 0; e < 4; ++e) { const float v = o[4 * n + e] + alpha * acc[ai][bj][m][n][e]; o[4 * n + e] = v; ss += v * v; }
;                     if (OUT_BF16) { u32x4 w; w.x = pk2(o[0], o[1]); w.y = pk2(o[2], o[3]); w.z = pk2(o[4], o[5]); w.w = pk2(o[6], o[7]); *(u32x4*)((bf16_t*)out + off) = w; }
;                     else { *(f32x4*)((float*)out + off) = (f32x4){o[0], o[1], o[2], o[3]}; *(f32x4*)((float*)out + off + 4) = (f32x4){o[4], o[5], o[6], o[7]}; }
;                 }
;                 if (sumsq) { ss += __shfl_xor(ss, 16); ss += __shfl_xor(ss, 32); if (fq == 0) atomicAdd(sumsq + row, ss); }
.LBB0_701:
	v_lshl_add_u32 v146, s22, 8, v148
	v_lshl_or_b32 v144, s24, 8, v150
	v_ashrrev_i32_e32 v147, 31, v146
	v_ashrrev_i32_e32 v145, 31, v144
	v_lshlrev_b64 v[156:157], 10, v[146:147]
	v_lshl_add_u64 v[156:157], v[156:157], 0, v[144:145]
	v_readlane_b32 s22, v235, 31
	v_lshlrev_b64 v[160:161], 1, v[156:157]
	v_readlane_b32 s23, v235, 32
	v_lshl_add_u64 v[162:163], s[8:9], 0, v[160:161]
	s_nop 0
	v_lshl_add_u64 v[156:157], s[22:23], 0, v[160:161]
	s_mov_b64 s[98:99], 0x8000
	s_mov_b64 s[100:101], 0x28000
	v_mov_b32_e32 v232, v156
	v_mov_b32_e32 v233, v157
	global_load_dwordx4 v[170:173], v[232:233], off
	global_load_dwordx4 v[174:177], v[232:233], off offset:256
	v_lshl_add_u64 v[232:233], v[232:233], 0, s[98:99]
	global_load_dwordx4 v[178:181], v[232:233], off
	global_load_dwordx4 v[182:185], v[232:233], off offset:256
	v_lshl_add_u64 v[232:233], v[232:233], 0, s[98:99]
	global_load_dwordx4 v[192:195], v[232:233], off
	global_load_dwordx4 v[196:199], v[232:233], off offset:256
	v_lshl_add_u64 v[232:233], v[232:233], 0, s[98:99]
	global_load_dwordx4 v[200:203], v[232:233], off
	global_load_dwordx4 v[204:207], v[232:233], off offset:256
	v_lshl_add_u64 v[232:233], v[232:233], 0, s[100:101]
	global_load_dwordx4 v[208:211], v[232:233], off
	global_load_dwordx4 v[212:215], v[232:233], off offset:256
	v_lshl_add_u64 v[232:233], v[232:233], 0, s[98:99]
	global_load_dwordx4 v[216:219], v[232:233], off
	global_load_dwordx4 v[220:223], v[232:233], off offset:256
	v_lshl_add_u64 v[232:233], v[232:233], 0, s[98:99]
	global_load_dwordx4 v[224:227], v[232:233], off
	global_load_dwordx4 v[228:231], v[232:233], off offset:256
	v_lshl_add_u64 v[232:233], v[232:233], 0, s[98:99]
	global_load_dwordx4 v[236:239], v[232:233], off
	global_load_dwordx4 v[240:243], v[232:233], off offset:256
	v_or_b32_e32 v160, 0x100, v160
	v_lshl_add_u64 v[164:165], s[22:23], 0, v[160:161]
	s_waitcnt vmcnt(15)
	v_mov_b32_e32 v156, v170
	v_mov_b32_e32 v157, v171
	v_mov_b32_e32 v158, v172
	v_mov_b32_e32 v159, v173
	v_lshlrev_b32_e32 v155, 16, v156
	v_and_b32_e32 v156, 0xffff0000, v156
	v_lshlrev_b32_e32 v166, 16, v157
	v_and_b32_e32 v157, 0xffff0000, v157
	v_lshlrev_b32_e32 v167, 16, v158
	v_and_b32_e32 v158, 0xffff0000, v158
	v_lshlrev_b32_e32 v168, 16, v159
	v_and_b32_e32 v159, 0xffff0000, v159
	v_add_f32_e32 v155, v124, v155
	v_add_f32_e32 v169, v125, v156
	v_add_f32_e32 v126, v126, v166
	v_add_f32_e32 v127, v127, v157
	v_add_f32_e32 v166, v120, v167
	v_add_f32_e32 v121, v121, v158
	v_add_f32_e32 v167, v122, v168
	v_add_f32_e32 v168, v123, v159
	v_cvt_pk_bf16_f32 v122, v155, v169
	v_cvt_pk_bf16_f32 v123, v126, v127
	v_cvt_pk_bf16_f32 v124, v166, v121
	v_cvt_pk_bf16_f32 v125, v167, v168
	s_nop 0
	v_mul_f32_e32 v169, v169, v169
	v_fmac_f32_e32 v169, v155, v155
	v_fmac_f32_e32 v169, v126, v126
	v_fmac_f32_e32 v169, v127, v127
	v_fmac_f32_e32 v169, v166, v166
	v_fmac_f32_e32 v169, v121, v121
	v_fmac_f32_e32 v169, v167, v167
	v_fmac_f32_e32 v169, v168, v168
	v_and_b32_e32 v164, 64, v154
	v_xor_b32_e32 v120, 16, v154
	v_add_u32_e32 v164, 64, v164
	v_cmp_lt_i32_e32 vcc, v120, v164
	v_xor_b32_e32 v165, 32, v154
	global_store_dwordx4 v[162:163], v[122:125], off
	v_cndmask_b32_e32 v120, v154, v120, vcc
	v_lshlrev_b32_e32 v120, 2, v120
	v_cmp_lt_i32_e32 vcc, v165, v164
	v_lshl_add_u64 v[122:123], s[8:9], 0, v[160:161]
	s_waitcnt vmcnt(15)
	v_mov_b32_e32 v156, v174
	v_mov_b32_e32 v157, v175
	v_mov_b32_e32 v158, v176
	v_mov_b32_e32 v159, v177
	v_lshlrev_b32_e32 v121, 16, v156
	v_and_b32_e32 v126, 0xffff0000, v156
	v_add_f32_e32 v116, v116, v121
	v_lshlrev_b32_e32 v127, 16, v157
	v_add_f32_e32 v117, v117, v126
	v_fmac_f32_e32 v169, v116, v116
	v_and_b32_e32 v155, 0xffff0000, v157
	v_add_f32_e32 v118, v118, v127
	v_fmac_f32_e32 v169, v117, v117
	v_lshlrev_b32_e32 v156, 16, v158
	v_add_f32_e32 v119, v119, v155
	v_fmac_f32_e32 v169, v118, v118
	v_and_b32_e32 v157, 0xffff0000, v158
	v_add_f32_e32 v121, v112, v156
	v_fmac_f32_e32 v169, v119, v119
	v_lshlrev_b32_e32 v158, 16, v159
	v_add_f32_e32 v126, v113, v157
	v_fmac_f32_e32 v169, v121, v121
	v_and_b32_e32 v159, 0xffff0000, v159
	v_add_f32_e32 v127, v114, v158
	v_fmac_f32_e32 v169, v126, v126
	v_add_f32_e32 v115, v115, v159
	v_fmac_f32_e32 v169, v127, v127
	v_fmac_f32_e32 v169, v115, v115
	ds_bpermute_b32 v112, v120, v169
	v_cndmask_b32_e32 v113, v154, v165, vcc
	v_lshlrev_b32_e32 v114, 2, v113
	v_cvt_pk_bf16_f32 v116, v116, v117
	v_cvt_pk_bf16_f32 v117, v118, v119
	s_waitcnt lgkmcnt(0)
	v_add_f32_e32 v112, v169, v112
	ds_bpermute_b32 v113, v114, v112
	v_cvt_pk_bf16_f32 v118, v121, v126
	v_cvt_pk_bf16_f32 v119, v127, v115
	global_store_dwordx4 v[122:123], v[116:119], off
	s_and_saveexec_b64 s[22:23], s[4:5]
	s_cbranch_execz .LBB0_703
	v_lshl_add_u64 v[116:117], v[146:147], 2, s[10:11]
	s_waitcnt lgkmcnt(0)
	v_add_f32_e32 v112, v112, v113
	global_atomic_add_f32 v[116:117], v112, off
; __device__ __forceinline__ unsigned pk2(float lo, float hi) { return pg8::cvt_pk_bf16(lo, hi); }
;     __device__ __forceinline__ void operator()(const f32x4 (&acc)[2][2][4][2], const pg8::Unit& u, int wr, int wc, int fr, int fq) const {
;     ...
;                 const int row = row0 + ai * 128 + m * 16; float ss = 0.f;
; #pragma unroll
;                 for (int bj = 0; bj < 2; ++bj) {
;                     const size_t off = (size_t)row * DM + col0 + bj * 128;
;                     float o[8];
;                     if (BASE_BF16) { const u32x4 bw = *(const u32x4*)((const bf16_t*)base + off);
; #pragma unroll
;                         for (int e = 0; e < 4; ++e) { o[2 * e] = __uint_as_float(bw[e] << 16); o[2 * e + 1] = __uint_as_float(bw[e] & 0xffff0000u); } }
;                     else { const f32x4 b0 = *(const f32x4*)((const float*)base + off), b1 = *(const f32x4*)((const float*)base + off + 4);
; #pragma unroll
;                         for (int e = 0; e < 4; ++e) { o[e] = b0[e]; o[4 + e] = b1[e]; } }
; #pragma unroll
;                     for (int n = 0; n < 2; ++n)
; #pragma unroll
;                         for (int e = 0; e < 4; ++e) { const float v = o[4 * n + e] + alpha * acc[ai][bj][m][n][e]; o[4 * n + e] = v; ss += v * v; }
;                     if (OUT_BF16) { u32x4 w; w.x = pk2(o[0], o[1]); w.y = pk2(o[2], o[3]); w.z = pk2(o[4], o[5]); w.w = pk2(o[6], o[7]); *(u32x4*)((bf16_t*)out + off) = w; }
;                     else { *(f32x4*)((float*)out + off) = (f32x4){o[0], o[1], o[2], o[3]}; *(f32x4*)((float*)out + off + 4) = (f32x4){o[4], o[5], o[6], o[7]}; }
;                 }
;                 if (sumsq) { ss += __shfl_xor(ss, 16); ss += __shfl_xor(ss, 32); if (fq == 0) atomicAdd(sumsq + row, ss); }
.LBB0_703:
	s_or_b64 exec, exec, s[22:23]
	v_or_b32_e32 v112, 16, v146
	s_waitcnt lgkmcnt(0)
	v_ashrrev_i32_e32 v113, 31, v112
	v_lshlrev_b64 v[116:117], 10, v[112:113]
	v_lshl_add_u64 v[116:117], v[116:117], 0, v[144:145]
	v_readlane_b32 s22, v235, 31
	v_lshlrev_b64 v[122:123], 1, v[116:117]
	v_readlane_b32 s23, v235, 32
	v_lshl_add_u64 v[124:125], s[8:9], 0, v[122:123]
	s_nop 0
	v_lshl_add_u64 v[116:117], s[22:23], 0, v[122:123]
	s_nop 0
	v_or_b32_e32 v122, 0x100, v122
	v_lshl_add_u64 v[126:127], s[22:23], 0, v[122:123]
	s_waitcnt vmcnt(15)
	v_mov_b32_e32 v116, v178
	v_mov_b32_e32 v117, v179
	v_mov_b32_e32 v118, v180
	v_mov_b32_e32 v119, v181
	v_lshlrev_b32_e32 v115, 16, v116
	v_and_b32_e32 v116, 0xffff0000, v116
	v_lshlrev_b32_e32 v121, 16, v117
	v_and_b32_e32 v117, 0xffff0000, v117
	v_lshlrev_b32_e32 v147, 16, v118
	v_and_b32_e32 v118, 0xffff0000, v118
	v_lshlrev_b32_e32 v155, 16, v119
	v_and_b32_e32 v119, 0xffff0000, v119
	v_add_f32_e32 v115, v108, v115
	v_add_f32_e32 v116, v109, v116
	v_add_f32_e32 v121, v110, v121
	v_add_f32_e32 v117, v111, v117
	v_add_f32_e32 v147, v104, v147
	v_add_f32_e32 v118, v105, v118
	v_add_f32_e32 v155, v106, v155
	v_add_f32_e32 v119, v107, v119
	v_cvt_pk_bf16_f32 v104, v115, v116
	v_cvt_pk_bf16_f32 v105, v121, v117
	v_cvt_pk_bf16_f32 v106, v147, v118
	v_cvt_pk_bf16_f32 v107, v155, v119
	s_nop 0
	v_mul_f32_e32 v116, v116, v116
	v_fmac_f32_e32 v116, v115, v115
	v_fmac_f32_e32 v116, v121, v121
	v_fmac_f32_e32 v116, v117, v117
	v_fmac_f32_e32 v116, v147, v147
	v_fmac_f32_e32 v116, v118, v118
	v_fmac_f32_e32 v116, v155, v155
	v_fmac_f32_e32 v116, v119, v119
	global_store_dwordx4 v[124:125], v[104:107], off
	s_waitcnt vmcnt(15)
	v_mov_b32_e32 v108, v182
	v_mov_b32_e32 v109, v183
	v_mov_b32_e32 v110, v184
	v_mov_b32_e32 v111, v185
	v_lshlrev_b32_e32 v115, 16, v108
	v_and_b32_e32 v108, 0xffff0000, v108
	v_add_f32_e32 v100, v100, v115
	v_lshlrev_b32_e32 v117, 16, v109
	v_add_f32_e32 v101, v101, v108
	v_fmac_f32_e32 v116, v100, v100
	v_and_b32_e32 v109, 0xffff0000, v109
	v_add_f32_e32 v102, v102, v117
	v_fmac_f32_e32 v116, v101, v101
	v_lshlrev_b32_e32 v118, 16, v110
	v_add_f32_e32 v103, v103, v109
	v_fmac_f32_e32 v116, v102, v102
	v_and_b32_e32 v110, 0xffff0000, v110
	v_add_f32_e32 v108, v96, v118
	v_fmac_f32_e32 v116, v103, v103
	v_lshlrev_b32_e32 v121, 16, v111
	v_add_f32_e32 v109, v97, v110
	v_fmac_f32_e32 v116, v108, v108
	v_and_b32_e32 v111, 0xffff0000, v111
	v_add_f32_e32 v110, v98, v121
	v_fmac_f32_e32 v116, v109, v109
	v_add_f32_e32 v111, v99, v111
	v_fmac_f32_e32 v116, v110, v110
	v_fmac_f32_e32 v116, v111, v111
	ds_bpermute_b32 v96, v120, v116
	v_cvt_pk_bf16_f32 v98, v100, v101
	v_cvt_pk_bf16_f32 v99, v102, v103
	v_lshl_add_u64 v[102:103], s[8:9], 0, v[122:123]
	v_cvt_pk_bf16_f32 v100, v108, v109
	s_waitcnt lgkmcnt(0)
	v_add_f32_e32 v96, v116, v96
	ds_bpermute_b32 v97, v114, v96
	v_cvt_pk_bf16_f32 v101, v110, v111
	global_store_dwordx4 v[102:103], v[98:101], off
	s_and_saveexec_b64 s[22:23], s[4:5]
	s_cbranch_execz .LBB0_705
	v_lshl_add_u64 v[98:99], v[112:113], 2, s[10:11]
	s_waitcnt lgkmcnt(0)
	v_add_f32_e32 v96, v96, v97
	global_atomic_add_f32 v[98:99], v96, off
.LBB0_705:
	s_or_b64 exec, exec, s[22:23]
	v_or_b32_e32 v96, 32, v146
	s_waitcnt lgkmcnt(0)
	v_ashrrev_i32_e32 v97, 31, v96
	v_lshlrev_b64 v[98:99], 10, v[96:97]
	v_lshl_add_u64 v[98:99], v[98:99], 0, v[144:145]
	v_readlane_b32 s22, v235, 31
	v_lshlrev_b64 v[102:103], 1, v[98:99]
	v_readlane_b32 s23, v235, 32
	v_lshl_add_u64 v[104:105], s[8:9], 0, v[102:103]
	s_nop 0
	v_lshl_add_u64 v[98:99], s[22:23], 0, v[102:103]
	s_nop 0
	v_or_b32_e32 v102, 0x100, v102
	v_lshl_add_u64 v[106:107], s[22:23], 0, v[102:103]
	s_waitcnt vmcnt(15)
	v_mov_b32_e32 v98, v192
	v_mov_b32_e32 v99, v193
	v_mov_b32_e32 v100, v194
	v_mov_b32_e32 v101, v195
	v_lshlrev_b32_e32 v108, 16, v98
	v_and_b32_e32 v98, 0xffff0000, v98
	v_lshlrev_b32_e32 v109, 16, v99
	v_and_b32_e32 v99, 0xffff0000, v99
	v_lshlrev_b32_e32 v110, 16, v100
	v_and_b32_e32 v100, 0xffff0000, v100
	v_lshlrev_b32_e32 v111, 16, v101
	v_and_b32_e32 v101, 0xffff0000, v101
	v_add_f32_e32 v108, v92, v108
	v_add_f32_e32 v98, v93, v98
	v_add_f32_e32 v109, v94, v109
	v_add_f32_e32 v99, v95, v99
	v_add_f32_e32 v110, v88, v110
	v_add_f32_e32 v100, v89, v100
	v_add_f32_e32 v111, v90, v111
	v_add_f32_e32 v101, v91, v101
	v_cvt_pk_bf16_f32 v88, v108, v98
	v_cvt_pk_bf16_f32 v89, v109, v99
	v_cvt_pk_bf16_f32 v90, v110, v100
	v_cvt_pk_bf16_f32 v91, v111, v101
	s_nop 0
	v_mul_f32_e32 v98, v98, v98
	v_fmac_f32_e32 v98, v108, v108
	v_fmac_f32_e32 v98, v109, v109
	v_fmac_f32_e32 v98, v99, v99
	v_fmac_f32_e32 v98, v110, v110
	v_fmac_f32_e32 v98, v100, v100
	v_fmac_f32_e32 v98, v111, v111
	v_fmac_f32_e32 v98, v101, v101
	global_store_dwordx4 v[104:105], v[88:91], off
	s_waitcnt vmcnt(15)
	v_mov_b32_e32 v92, v196
	v_mov_b32_e32 v93, v197
	v_mov_b32_e32 v94, v198
	v_mov_b32_e32 v95, v199
	v_lshlrev_b32_e32 v99, 16, v92
	v_and_b32_e32 v92, 0xffff0000, v92
	v_add_f32_e32 v84, v84, v99
	v_lshlrev_b32_e32 v100, 16, v93
	v_add_f32_e32 v85, v85, v92
	v_fmac_f32_e32 v98, v84, v84
	v_and_b32_e32 v93, 0xffff0000, v93
	v_add_f32_e32 v86, v86, v100
	v_fmac_f32_e32 v98, v85, v85
	v_lshlrev_b32_e32 v106, 16, v94
	v_add_f32_e32 v87, v87, v93
	v_fmac_f32_e32 v98, v86, v86
	v_and_b32_e32 v94, 0xffff0000, v94
	v_add_f32_e32 v92, v80, v106
	v_fmac_f32_e32 v98, v87, v87
	v_lshlrev_b32_e32 v107, 16, v95
	v_add_f32_e32 v93, v81, v94
	v_fmac_f32_e32 v98, v92, v92
	v_and_b32_e32 v95, 0xffff0000, v95
	v_add_f32_e32 v94, v82, v107
	v_fmac_f32_e32 v98, v93, v93
	v_add_f32_e32 v95, v83, v95
	v_fmac_f32_e32 v98, v94, v94
	v_fmac_f32_e32 v98, v95, v95
	ds_bpermute_b32 v80, v120, v98
	v_cvt_pk_bf16_f32 v82, v84, v85
	v_cvt_pk_bf16_f32 v83, v86, v87
	v_lshl_add_u64 v[86:87], s[8:9], 0, v[102:103]
	v_cvt_pk_bf16_f32 v84, v92, v93
	s_waitcnt lgkmcnt(0)
	v_add_f32_e32 v80, v98, v80
	ds_bpermute_b32 v81, v114, v80
	v_cvt_pk_bf16_f32 v85, v94, v95
	global_store_dwordx4 v[86:87], v[82:85], off
	s_and_saveexec_b64 s[22:23], s[4:5]
	s_cbranch_execz .LBB0_707
	v_lshl_add_u64 v[82:83], v[96:97], 2, s[10:11]
	s_waitcnt lgkmcnt(0)
	v_add_f32_e32 v80, v80, v81
	global_atomic_add_f32 v[82:83], v80, off
; __device__ __forceinline__ unsigned pk2(float lo, float hi) { return pg8::cvt_pk_bf16(lo, hi); }
;     __device__ __forceinline__ void operator()(const f32x4 (&acc)[2][2][4][2], const pg8::Unit& u, int wr, int wc, int fr, int fq) const {
;     ...
;                 const int row = row0 + ai * 128 + m * 16; float ss = 0.f;
; #pragma unroll
;                 for (int bj = 0; bj < 2; ++bj) {
;                     const size_t off = (size_t)row * DM + col0 + bj * 128;
;                     float o[8];
;                     if (BASE_BF16) { const u32x4 bw = *(const u32x4*)((const bf16_t*)base + off);
; #pragma unroll
;                         for (int e = 0; e < 4; ++e) { o[2 * e] = __uint_as_float(bw[e] << 16); o[2 * e + 1] = __uint_as_float(bw[e] & 0xffff0000u); } }
;                     else { const f32x4 b0 = *(const f32x4*)((const float*)base + off), b1 = *(const f32x4*)((const float*)base + off + 4);
; #pragma unroll
;                         for (int e = 0; e < 4; ++e) { o[e] = b0[e]; o[4 + e] = b1[e]; } }
; #pragma unroll
;                     for (int n = 0; n < 2; ++n)
; #pragma unroll
;                         for (int e = 0; e < 4; ++e) { const float v = o[4 * n + e] + alpha * acc[ai][bj][m][n][e]; o[4 * n + e] = v; ss += v * v; }
;                     if (OUT_BF16) { u32x4 w; w.x = pk2(o[0], o[1]); w.y = pk2(o[2], o[3]); w.z = pk2(o[4], o[5]); w.w = pk2(o[6], o[7]); *(u32x4*)((bf16_t*)out + off) = w; }
;                     else { *(f32x4*)((float*)out + off) = (f32x4){o[0], o[1], o[2], o[3]}; *(f32x4*)((float*)out + off + 4) = (f32x4){o[4], o[5], o[6], o[7]}; }
;                 }
;                 if (sumsq) { ss += __shfl_xor(ss, 16); ss += __shfl_xor(ss, 32); if (fq == 0) atomicAdd(sumsq + row, ss); }
.LBB0_707:
	s_or_b64 exec, exec, s[22:23]
	v_or_b32_e32 v80, 48, v146
	s_waitcnt lgkmcnt(0)
	v_ashrrev_i32_e32 v81, 31, v80
	v_lshlrev_b64 v[82:83], 10, v[80:81]
	v_lshl_add_u64 v[82:83], v[82:83], 0, v[144:145]
	v_readlane_b32 s22, v235, 31
	v_lshlrev_b64 v[86:87], 1, v[82:83]
	v_readlane_b32 s23, v235, 32
	v_lshl_add_u64 v[88:89], s[8:9], 0, v[86:87]
	s_nop 0
	v_lshl_add_u64 v[82:83], s[22:23], 0, v[86:87]
	s_nop 0
	v_or_b32_e32 v86, 0x100, v86
	v_lshl_add_u64 v[90:91], s[22:23], 0, v[86:87]
	s_waitcnt vmcnt(15)
	v_mov_b32_e32 v82, v200
	v_mov_b32_e32 v83, v201
	v_mov_b32_e32 v84, v202
	v_mov_b32_e32 v85, v203
	v_lshlrev_b32_e32 v92, 16, v82
	v_and_b32_e32 v82, 0xffff0000, v82
	v_lshlrev_b32_e32 v93, 16, v83
	v_and_b32_e32 v83, 0xffff0000, v83
	v_lshlrev_b32_e32 v94, 16, v84
	v_and_b32_e32 v84, 0xffff0000, v84
	v_lshlrev_b32_e32 v95, 16, v85
	v_and_b32_e32 v85, 0xffff0000, v85
	v_add_f32_e32 v92, v76, v92
	v_add_f32_e32 v82, v77, v82
	v_add_f32_e32 v93, v78, v93
	v_add_f32_e32 v83, v79, v83
	v_add_f32_e32 v94, v72, v94
	v_add_f32_e32 v84, v73, v84
	v_add_f32_e32 v95, v74, v95
	v_add_f32_e32 v85, v75, v85
	v_cvt_pk_bf16_f32 v72, v92, v82
	v_cvt_pk_bf16_f32 v73, v93, v83
	v_cvt_pk_bf16_f32 v74, v94, v84
	v_cvt_pk_bf16_f32 v75, v95, v85
	s_nop 0
	v_mul_f32_e32 v82, v82, v82
	v_fmac_f32_e32 v82, v92, v92
	v_fmac_f32_e32 v82, v93, v93
	v_fmac_f32_e32 v82, v83, v83
	v_fmac_f32_e32 v82, v94, v94
	v_fmac_f32_e32 v82, v84, v84
	v_fmac_f32_e32 v82, v95, v95
	v_fmac_f32_e32 v82, v85, v85
	global_store_dwordx4 v[88:89], v[72:75], off
	s_waitcnt vmcnt(15)
	v_mov_b32_e32 v76, v204
	v_mov_b32_e32 v77, v205
	v_mov_b32_e32 v78, v206
	v_mov_b32_e32 v79, v207
	v_lshlrev_b32_e32 v83, 16, v76
	v_and_b32_e32 v76, 0xffff0000, v76
	v_add_f32_e32 v68, v68, v83
	v_lshlrev_b32_e32 v84, 16, v77
	v_add_f32_e32 v69, v69, v76
	v_fmac_f32_e32 v82, v68, v68
	v_and_b32_e32 v77, 0xffff0000, v77
	v_add_f32_e32 v70, v70, v84
	v_fmac_f32_e32 v82, v69, v69
	v_lshlrev_b32_e32 v90, 16, v78
	v_add_f32_e32 v71, v71, v77
	v_fmac_f32_e32 v82, v70, v70
	v_and_b32_e32 v78, 0xffff0000, v78
	v_add_f32_e32 v76, v64, v90
	v_fmac_f32_e32 v82, v71, v71
	v_lshlrev_b32_e32 v91, 16, v79
	v_add_f32_e32 v77, v65, v78
	v_fmac_f32_e32 v82, v76, v76
	v_and_b32_e32 v79, 0xffff0000, v79
	v_add_f32_e32 v78, v66, v91
	v_fmac_f32_e32 v82, v77, v77
	v_add_f32_e32 v79, v67, v79
	v_fmac_f32_e32 v82, v78, v78
	v_fmac_f32_e32 v82, v79, v79
	ds_bpermute_b32 v64, v120, v82
	v_cvt_pk_bf16_f32 v66, v68, v69
	v_cvt_pk_bf16_f32 v67, v70, v71
	v_lshl_add_u64 v[70:71], s[8:9], 0, v[86:87]
	v_cvt_pk_bf16_f32 v68, v76, v77
	s_waitcnt lgkmcnt(0)
	v_add_f32_e32 v64, v82, v64
	ds_bpermute_b32 v65, v114, v64
	v_cvt_pk_bf16_f32 v69, v78, v79
	global_store_dwordx4 v[70:71], v[66:69], off
	s_and_saveexec_b64 s[22:23], s[4:5]
	s_cbranch_execz .LBB0_709
	v_lshl_add_u64 v[66:67], v[80:81], 2, s[10:11]
	s_waitcnt lgkmcnt(0)
	v_add_f32_e32 v64, v64, v65
	global_atomic_add_f32 v[66:67], v64, off
.LBB0_709:
	s_or_b64 exec, exec, s[22:23]
	v_add_u32_e32 v64, 0x80, v146
	s_waitcnt lgkmcnt(0)
	v_ashrrev_i32_e32 v65, 31, v64
	v_lshlrev_b64 v[66:67], 10, v[64:65]
	v_lshl_add_u64 v[66:67], v[66:67], 0, v[144:145]
	v_readlane_b32 s22, v235, 31
	v_lshlrev_b64 v[70:71], 1, v[66:67]
	v_readlane_b32 s23, v235, 32
	v_lshl_add_u64 v[72:73], s[8:9], 0, v[70:71]
	s_nop 0
	v_lshl_add_u64 v[66:67], s[22:23], 0, v[70:71]
	s_nop 0
	v_or_b32_e32 v70, 0x100, v70
	v_lshl_add_u64 v[74:75], s[22:23], 0, v[70:71]
	s_waitcnt vmcnt(15)
	v_mov_b32_e32 v66, v208
	v_mov_b32_e32 v67, v209
	v_mov_b32_e32 v68, v210
	v_mov_b32_e32 v69, v211
	v_lshlrev_b32_e32 v76, 16, v66
	v_and_b32_e32 v66, 0xffff0000, v66
	v_lshlrev_b32_e32 v77, 16, v67
	v_and_b32_e32 v67, 0xffff0000, v67
	v_lshlrev_b32_e32 v78, 16, v68
	v_and_b32_e32 v68, 0xffff0000, v68
	v_lshlrev_b32_e32 v79, 16, v69
	v_and_b32_e32 v69, 0xffff0000, v69
	v_add_f32_e32 v76, v60, v76
	v_add_f32_e32 v66, v61, v66
	v_add_f32_e32 v77, v62, v77
	v_add_f32_e32 v67, v63, v67
	v_add_f32_e32 v78, v56, v78
	v_add_f32_e32 v68, v57, v68
	v_add_f32_e32 v79, v58, v79
	v_add_f32_e32 v69, v59, v69
	v_cvt_pk_bf16_f32 v56, v76, v66
	v_cvt_pk_bf16_f32 v57, v77, v67
	v_cvt_pk_bf16_f32 v58, v78, v68
	v_cvt_pk_bf16_f32 v59, v79, v69
	s_nop 0
	v_mul_f32_e32 v66, v66, v66
	v_fmac_f32_e32 v66, v76, v76
	v_fmac_f32_e32 v66, v77, v77
	v_fmac_f32_e32 v66, v67, v67
	v_fmac_f32_e32 v66, v78, v78
	v_fmac_f32_e32 v66, v68, v68
	v_fmac_f32_e32 v66, v79, v79
	v_fmac_f32_e32 v66, v69, v69
	global_store_dwordx4 v[72:73], v[56:59], off
	s_waitcnt vmcnt(15)
	v_mov_b32_e32 v60, v212
	v_mov_b32_e32 v61, v213
	v_mov_b32_e32 v62, v214
	v_mov_b32_e32 v63, v215
	v_lshlrev_b32_e32 v67, 16, v60
	v_and_b32_e32 v60, 0xffff0000, v60
	v_add_f32_e32 v52, v52, v67
	v_lshlrev_b32_e32 v68, 16, v61
	v_add_f32_e32 v53, v53, v60
	v_fmac_f32_e32 v66, v52, v52
	v_and_b32_e32 v61, 0xffff0000, v61
	v_add_f32_e32 v54, v54, v68
	v_fmac_f32_e32 v66, v53, v53
	v_lshlrev_b32_e32 v74, 16, v62
	v_add_f32_e32 v55, v55, v61
	v_fmac_f32_e32 v66, v54, v54
	v_and_b32_e32 v62, 0xffff0000, v62
	v_add_f32_e32 v60, v48, v74
	v_fmac_f32_e32 v66, v55, v55
	v_lshlrev_b32_e32 v75, 16, v63
	v_add_f32_e32 v61, v49, v62
	v_fmac_f32_e32 v66, v60, v60
	v_and_b32_e32 v63, 0xffff0000, v63
	v_add_f32_e32 v62, v50, v75
	v_fmac_f32_e32 v66, v61, v61
	v_add_f32_e32 v63, v51, v63
	v_fmac_f32_e32 v66, v62, v62
	v_fmac_f32_e32 v66, v63, v63
	ds_bpermute_b32 v48, v120, v66
	v_cvt_pk_bf16_f32 v50, v52, v53
	v_cvt_pk_bf16_f32 v51, v54, v55
	v_lshl_add_u64 v[54:55], s[8:9], 0, v[70:71]
	v_cvt_pk_bf16_f32 v52, v60, v61
	s_waitcnt lgkmcnt(0)
	v_add_f32_e32 v48, v66, v48
	ds_bpermute_b32 v49, v114, v48
	v_cvt_pk_bf16_f32 v53, v62, v63
	global_store_dwordx4 v[54:55], v[50:53], off
	s_and_saveexec_b64 s[22:23], s[4:5]
	s_cbranch_execz .LBB0_711
	v_lshl_add_u64 v[50:51], v[64:65], 2, s[10:11]
	s_waitcnt lgkmcnt(0)
	v_add_f32_e32 v48, v48, v49
	global_atomic_add_f32 v[50:51], v48, off
; __device__ __forceinline__ unsigned pk2(float lo, float hi) { return pg8::cvt_pk_bf16(lo, hi); }
;     __device__ __forceinline__ void operator()(const f32x4 (&acc)[2][2][4][2], const pg8::Unit& u, int wr, int wc, int fr, int fq) const {
;     ...
;                 const int row = row0 + ai * 128 + m * 16; float ss = 0.f;
; #pragma unroll
;                 for (int bj = 0; bj < 2; ++bj) {
;                     const size_t off = (size_t)row * DM + col0 + bj * 128;
;                     float o[8];
;                     if (BASE_BF16) { const u32x4 bw = *(const u32x4*)((const bf16_t*)base + off);
; #pragma unroll
;                         for (int e = 0; e < 4; ++e) { o[2 * e] = __uint_as_float(bw[e] << 16); o[2 * e + 1] = __uint_as_float(bw[e] & 0xffff0000u); } }
;                     else { const f32x4 b0 = *(const f32x4*)((const float*)base + off), b1 = *(const f32x4*)((const float*)base + off + 4);
; #pragma unroll
;                         for (int e = 0; e < 4; ++e) { o[e] = b0[e]; o[4 + e] = b1[e]; } }
; #pragma unroll
;                     for (int n = 0; n < 2; ++n)
; #pragma unroll
;                         for (int e = 0; e < 4; ++e) { const float v = o[4 * n + e] + alpha * acc[ai][bj][m][n][e]; o[4 * n + e] = v; ss += v * v; }
;                     if (OUT_BF16) { u32x4 w; w.x = pk2(o[0], o[1]); w.y = pk2(o[2], o[3]); w.z = pk2(o[4], o[5]); w.w = pk2(o[6], o[7]); *(u32x4*)((bf16_t*)out + off) = w; }
;                     else { *(f32x4*)((float*)out + off) = (f32x4){o[0], o[1], o[2], o[3]}; *(f32x4*)((float*)out + off + 4) = (f32x4){o[4], o[5], o[6], o[7]}; }
;                 }
;                 if (sumsq) { ss += __shfl_xor(ss, 16); ss += __shfl_xor(ss, 32); if (fq == 0) atomicAdd(sumsq + row, ss); }
.LBB0_711:
	s_or_b64 exec, exec, s[22:23]
	v_add_u32_e32 v48, 0x90, v146
	s_waitcnt lgkmcnt(0)
	v_ashrrev_i32_e32 v49, 31, v48
	v_lshlrev_b64 v[50:51], 10, v[48:49]
	v_lshl_add_u64 v[50:51], v[50:51], 0, v[144:145]
	v_readlane_b32 s22, v235, 31
	v_lshlrev_b64 v[54:55], 1, v[50:51]
	v_readlane_b32 s23, v235, 32
	v_lshl_add_u64 v[56:57], s[8:9], 0, v[54:55]
	s_nop 0
	v_lshl_add_u64 v[50:51], s[22:23], 0, v[54:55]
	s_nop 0
	v_or_b32_e32 v54, 0x100, v54
	v_lshl_add_u64 v[58:59], s[22:23], 0, v[54:55]
	s_waitcnt vmcnt(15)
	v_mov_b32_e32 v50, v216
	v_mov_b32_e32 v51, v217
	v_mov_b32_e32 v52, v218
	v_mov_b32_e32 v53, v219
	v_lshlrev_b32_e32 v60, 16, v50
	v_and_b32_e32 v50, 0xffff0000, v50
	v_lshlrev_b32_e32 v61, 16, v51
	v_and_b32_e32 v51, 0xffff0000, v51
	v_lshlrev_b32_e32 v62, 16, v52
	v_and_b32_e32 v52, 0xffff0000, v52
	v_lshlrev_b32_e32 v63, 16, v53
	v_and_b32_e32 v53, 0xffff0000, v53
	v_add_f32_e32 v60, v44, v60
	v_add_f32_e32 v50, v45, v50
	v_add_f32_e32 v61, v46, v61
	v_add_f32_e32 v51, v47, v51
	v_add_f32_e32 v62, v40, v62
	v_add_f32_e32 v52, v41, v52
	v_add_f32_e32 v63, v42, v63
	v_add_f32_e32 v53, v43, v53
	v_cvt_pk_bf16_f32 v40, v60, v50
	v_cvt_pk_bf16_f32 v41, v61, v51
	v_cvt_pk_bf16_f32 v42, v62, v52
	v_cvt_pk_bf16_f32 v43, v63, v53
	s_nop 0
	v_mul_f32_e32 v50, v50, v50
	v_fmac_f32_e32 v50, v60, v60
	v_fmac_f32_e32 v50, v61, v61
	v_fmac_f32_e32 v50, v51, v51
	v_fmac_f32_e32 v50, v62, v62
	v_fmac_f32_e32 v50, v52, v52
	v_fmac_f32_e32 v50, v63, v63
	v_fmac_f32_e32 v50, v53, v53
	global_store_dwordx4 v[56:57], v[40:43], off
	s_waitcnt vmcnt(15)
	v_mov_b32_e32 v44, v220
	v_mov_b32_e32 v45, v221
	v_mov_b32_e32 v46, v222
	v_mov_b32_e32 v47, v223
	v_lshlrev_b32_e32 v51, 16, v44
	v_and_b32_e32 v44, 0xffff0000, v44
	v_add_f32_e32 v36, v36, v51
	v_lshlrev_b32_e32 v52, 16, v45
	v_add_f32_e32 v37, v37, v44
	v_fmac_f32_e32 v50, v36, v36
	v_and_b32_e32 v45, 0xffff0000, v45
	v_add_f32_e32 v38, v38, v52
	v_fmac_f32_e32 v50, v37, v37
	v_lshlrev_b32_e32 v58, 16, v46
	v_add_f32_e32 v39, v39, v45
	v_fmac_f32_e32 v50, v38, v38
	v_and_b32_e32 v46, 0xffff0000, v46
	v_add_f32_e32 v44, v32, v58
	v_fmac_f32_e32 v50, v39, v39
	v_lshlrev_b32_e32 v59, 16, v47
	v_add_f32_e32 v45, v33, v46
	v_fmac_f32_e32 v50, v44, v44
	v_and_b32_e32 v47, 0xffff0000, v47
	v_add_f32_e32 v46, v34, v59
	v_fmac_f32_e32 v50, v45, v45
	v_add_f32_e32 v47, v35, v47
	v_fmac_f32_e32 v50, v46, v46
	v_fmac_f32_e32 v50, v47, v47
	ds_bpermute_b32 v32, v120, v50
	v_cvt_pk_bf16_f32 v34, v36, v37
	v_cvt_pk_bf16_f32 v35, v38, v39
	v_lshl_add_u64 v[38:39], s[8:9], 0, v[54:55]
	v_cvt_pk_bf16_f32 v36, v44, v45
	s_waitcnt lgkmcnt(0)
	v_add_f32_e32 v32, v50, v32
	ds_bpermute_b32 v33, v114, v32
	v_cvt_pk_bf16_f32 v37, v46, v47
	global_store_dwordx4 v[38:39], v[34:37], off
	s_and_saveexec_b64 s[22:23], s[4:5]
	s_cbranch_execz .LBB0_713
	v_lshl_add_u64 v[34:35], v[48:49], 2, s[10:11]
	s_waitcnt lgkmcnt(0)
	v_add_f32_e32 v32, v32, v33
	global_atomic_add_f32 v[34:35], v32, off
; __device__ __forceinline__ unsigned pk2(float lo, float hi) { return pg8::cvt_pk_bf16(lo, hi); }
;     __device__ __forceinline__ void operator()(const f32x4 (&acc)[2][2][4][2], const pg8::Unit& u, int wr, int wc, int fr, int fq) const {
;     ...
;                 const int row = row0 + ai * 128 + m * 16; float ss = 0.f;
; #pragma unroll
;                 for (int bj = 0; bj < 2; ++bj) {
;                     const size_t off = (size_t)row * DM + col0 + bj * 128;
;                     float o[8];
;                     if (BASE_BF16) { const u32x4 bw = *(const u32x4*)((const bf16_t*)base + off);
; #pragma unroll
;                         for (int e = 0; e < 4; ++e) { o[2 * e] = __uint_as_float(bw[e] << 16); o[2 * e + 1] = __uint_as_float(bw[e] & 0xffff0000u); } }
;                     else { const f32x4 b0 = *(const f32x4*)((const float*)base + off), b1 = *(const f32x4*)((const float*)base + off + 4);
; #pragma unroll
;                         for (int e = 0; e < 4; ++e) { o[e] = b0[e]; o[4 + e] = b1[e]; } }
; #pragma unroll
;                     for (int n = 0; n < 2; ++n)
; #pragma unroll
;                         for (int e = 0; e < 4; ++e) { const float v = o[4 * n + e] + alpha * acc[ai][bj][m][n][e]; o[4 * n + e] = v; ss += v * v; }
;                     if (OUT_BF16) { u32x4 w; w.x = pk2(o[0], o[1]); w.y = pk2(o[2], o[3]); w.z = pk2(o[4], o[5]); w.w = pk2(o[6], o[7]); *(u32x4*)((bf16_t*)out + off) = w; }
;                     else { *(f32x4*)((float*)out + off) = (f32x4){o[0], o[1], o[2], o[3]}; *(f32x4*)((float*)out + off + 4) = (f32x4){o[4], o[5], o[6], o[7]}; }
;                 }
;                 if (sumsq) { ss += __shfl_xor(ss, 16); ss += __shfl_xor(ss, 32); if (fq == 0) atomicAdd(sumsq + row, ss); }
.LBB0_713:
	s_or_b64 exec, exec, s[22:23]
	v_add_u32_e32 v32, 0xa0, v146
	s_waitcnt lgkmcnt(0)
	v_ashrrev_i32_e32 v33, 31, v32
	v_lshlrev_b64 v[34:35], 10, v[32:33]
	v_lshl_add_u64 v[34:35], v[34:35], 0, v[144:145]
	v_readlane_b32 s22, v235, 31
	v_lshlrev_b64 v[38:39], 1, v[34:35]
	v_readlane_b32 s23, v235, 32
	v_lshl_add_u64 v[40:41], s[8:9], 0, v[38:39]
	s_nop 0
	v_lshl_add_u64 v[34:35], s[22:23], 0, v[38:39]
	s_nop 0
	v_or_b32_e32 v38, 0x100, v38
	v_lshl_add_u64 v[42:43], s[22:23], 0, v[38:39]
	s_waitcnt vmcnt(15)
	v_mov_b32_e32 v34, v224
	v_mov_b32_e32 v35, v225
	v_mov_b32_e32 v36, v226
	v_mov_b32_e32 v37, v227
	v_lshlrev_b32_e32 v44, 16, v34
	v_and_b32_e32 v34, 0xffff0000, v34
	v_lshlrev_b32_e32 v45, 16, v35
	v_and_b32_e32 v35, 0xffff0000, v35
	v_lshlrev_b32_e32 v46, 16, v36
	v_and_b32_e32 v36, 0xffff0000, v36
	v_lshlrev_b32_e32 v47, 16, v37
	v_and_b32_e32 v37, 0xffff0000, v37
	v_add_f32_e32 v44, v28, v44
	v_add_f32_e32 v34, v29, v34
	v_add_f32_e32 v45, v30, v45
	v_add_f32_e32 v35, v31, v35
	v_add_f32_e32 v46, v24, v46
	v_add_f32_e32 v36, v25, v36
	v_add_f32_e32 v47, v26, v47
	v_add_f32_e32 v37, v27, v37
	v_cvt_pk_bf16_f32 v24, v44, v34
	v_cvt_pk_bf16_f32 v25, v45, v35
	v_cvt_pk_bf16_f32 v26, v46, v36
	v_cvt_pk_bf16_f32 v27, v47, v37
	s_nop 0
	v_mul_f32_e32 v34, v34, v34
	v_fmac_f32_e32 v34, v44, v44
	v_fmac_f32_e32 v34, v45, v45
	v_fmac_f32_e32 v34, v35, v35
	v_fmac_f32_e32 v34, v46, v46
	v_fmac_f32_e32 v34, v36, v36
	v_fmac_f32_e32 v34, v47, v47
	v_fmac_f32_e32 v34, v37, v37
	global_store_dwordx4 v[40:41], v[24:27], off
	s_waitcnt vmcnt(15)
	v_mov_b32_e32 v28, v228
	v_mov_b32_e32 v29, v229
	v_mov_b32_e32 v30, v230
	v_mov_b32_e32 v31, v231
	v_lshlrev_b32_e32 v35, 16, v28
	v_and_b32_e32 v28, 0xffff0000, v28
	v_add_f32_e32 v20, v20, v35
	v_lshlrev_b32_e32 v36, 16, v29
	v_add_f32_e32 v21, v21, v28
	v_fmac_f32_e32 v34, v20, v20
	v_and_b32_e32 v29, 0xffff0000, v29
	v_add_f32_e32 v22, v22, v36
	v_fmac_f32_e32 v34, v21, v21
	v_lshlrev_b32_e32 v42, 16, v30
	v_add_f32_e32 v23, v23, v29
	v_fmac_f32_e32 v34, v22, v22
	v_and_b32_e32 v30, 0xffff0000, v30
	v_add_f32_e32 v28, v16, v42
	v_fmac_f32_e32 v34, v23, v23
	v_lshlrev_b32_e32 v43, 16, v31
	v_add_f32_e32 v29, v17, v30
	v_fmac_f32_e32 v34, v28, v28
	v_and_b32_e32 v31, 0xffff0000, v31
	v_add_f32_e32 v30, v18, v43
	v_fmac_f32_e32 v34, v29, v29
	v_add_f32_e32 v31, v19, v31
	v_fmac_f32_e32 v34, v30, v30
	v_fmac_f32_e32 v34, v31, v31
	ds_bpermute_b32 v16, v120, v34
	v_cvt_pk_bf16_f32 v18, v20, v21
	v_cvt_pk_bf16_f32 v19, v22, v23
	v_lshl_add_u64 v[22:23], s[8:9], 0, v[38:39]
	v_cvt_pk_bf16_f32 v20, v28, v29
	s_waitcnt lgkmcnt(0)
	v_add_f32_e32 v16, v34, v16
	ds_bpermute_b32 v17, v114, v16
	v_cvt_pk_bf16_f32 v21, v30, v31
	global_store_dwordx4 v[22:23], v[18:21], off
	s_and_saveexec_b64 s[22:23], s[4:5]
	s_cbranch_execz .LBB0_715
	v_lshl_add_u64 v[18:19], v[32:33], 2, s[10:11]
	s_waitcnt lgkmcnt(0)
	v_add_f32_e32 v16, v16, v17
	global_atomic_add_f32 v[18:19], v16, off
.LBB0_715:
	s_or_b64 exec, exec, s[22:23]
	v_add_u32_e32 v16, 0xb0, v146
	s_waitcnt lgkmcnt(0)
	v_ashrrev_i32_e32 v17, 31, v16
	v_lshlrev_b64 v[18:19], 10, v[16:17]
	v_lshl_add_u64 v[18:19], v[18:19], 0, v[144:145]
	v_readlane_b32 s22, v235, 31
	v_lshlrev_b64 v[22:23], 1, v[18:19]
	v_readlane_b32 s23, v235, 32
	v_lshl_add_u64 v[24:25], s[8:9], 0, v[22:23]
	s_nop 0
	v_lshl_add_u64 v[18:19], s[22:23], 0, v[22:23]
	s_nop 0
	v_or_b32_e32 v22, 0x100, v22
	v_lshl_add_u64 v[26:27], s[22:23], 0, v[22:23]
	s_waitcnt vmcnt(15)
	v_mov_b32_e32 v18, v236
	v_mov_b32_e32 v19, v237
	v_mov_b32_e32 v20, v238
	v_mov_b32_e32 v21, v239
	v_lshlrev_b32_e32 v28, 16, v18
	v_and_b32_e32 v18, 0xffff0000, v18
	v_lshlrev_b32_e32 v29, 16, v19
	v_and_b32_e32 v19, 0xffff0000, v19
	v_lshlrev_b32_e32 v30, 16, v20
	v_and_b32_e32 v20, 0xffff0000, v20
	v_lshlrev_b32_e32 v31, 16, v21
	v_and_b32_e32 v21, 0xffff0000, v21
	v_add_f32_e32 v28, v12, v28
	v_add_f32_e32 v18, v13, v18
	v_add_f32_e32 v29, v14, v29
	v_add_f32_e32 v19, v15, v19
	v_add_f32_e32 v30, v8, v30
	v_add_f32_e32 v20, v9, v20
	v_add_f32_e32 v31, v10, v31
	v_add_f32_e32 v21, v11, v21
	v_cvt_pk_bf16_f32 v8, v28, v18
	v_cvt_pk_bf16_f32 v9, v29, v19
	v_cvt_pk_bf16_f32 v10, v30, v20
	v_cvt_pk_bf16_f32 v11, v31, v21
	s_nop 0
	v_mul_f32_e32 v18, v18, v18
	v_fmac_f32_e32 v18, v28, v28
	v_fmac_f32_e32 v18, v29, v29
	v_fmac_f32_e32 v18, v19, v19
	v_fmac_f32_e32 v18, v30, v30
	v_fmac_f32_e32 v18, v20, v20
	v_fmac_f32_e32 v18, v31, v31
	v_fmac_f32_e32 v18, v21, v21
	global_store_dwordx4 v[24:25], v[8:11], off
	s_waitcnt vmcnt(15)
	v_mov_b32_e32 v12, v240
	v_mov_b32_e32 v13, v241
	v_mov_b32_e32 v14, v242
	v_mov_b32_e32 v15, v243
	v_lshlrev_b32_e32 v19, 16, v12
	v_and_b32_e32 v12, 0xffff0000, v12
	v_add_f32_e32 v4, v4, v19
	v_lshlrev_b32_e32 v20, 16, v13
	v_add_f32_e32 v5, v5, v12
	v_fmac_f32_e32 v18, v4, v4
	v_and_b32_e32 v13, 0xffff0000, v13
	v_add_f32_e32 v6, v6, v20
	v_fmac_f32_e32 v18, v5, v5
	v_lshlrev_b32_e32 v26, 16, v14
	v_add_f32_e32 v7, v7, v13
	v_fmac_f32_e32 v18, v6, v6
	v_and_b32_e32 v14, 0xffff0000, v14
	v_add_f32_e32 v12, v0, v26
	v_fmac_f32_e32 v18, v7, v7
	v_lshlrev_b32_e32 v27, 16, v15
	v_add_f32_e32 v13, v1, v14
	v_fmac_f32_e32 v18, v12, v12
	v_and_b32_e32 v15, 0xffff0000, v15
	v_add_f32_e32 v14, v2, v27
	v_fmac_f32_e32 v18, v13, v13
	v_add_f32_e32 v15, v3, v15
	v_fmac_f32_e32 v18, v14, v14
	v_fmac_f32_e32 v18, v15, v15
	ds_bpermute_b32 v0, v120, v18
	v_cvt_pk_bf16_f32 v2, v4, v5
	v_cvt_pk_bf16_f32 v3, v6, v7
	v_lshl_add_u64 v[6:7], s[8:9], 0, v[22:23]
	v_cvt_pk_bf16_f32 v4, v12, v13
	s_waitcnt lgkmcnt(0)
	v_add_f32_e32 v0, v18, v0
	ds_bpermute_b32 v1, v114, v0
	v_cvt_pk_bf16_f32 v5, v14, v15
	global_store_dwordx4 v[6:7], v[2:5], off
	s_and_saveexec_b64 s[22:23], s[4:5]
	s_cbranch_execz .LBB0_717
	v_lshl_add_u64 v[2:3], v[16:17], 2, s[10:11]
	s_waitcnt lgkmcnt(0)
	v_add_f32_e32 v0, v0, v1
	global_atomic_add_f32 v[2:3], v0, off
